# prefix loop 16 loads in flight with counted vmcnt; x_phase copy loop 8 items per iteration (16 loads in flight)
# speedup vs baseline: 1.0064x; 1.0001x over previous
.LBB0_109:
	global_load_dwordx4 v[20:23], v[6:7], off
	global_load_dwordx4 v[24:27], v[6:7], off offset:16
	v_add_u32_e32 v8, s38, v8
	v_lshl_add_u64 v[6:7], v[6:7], 0, s[6:7]
	global_load_dwordx4 v[28:31], v[6:7], off
	global_load_dwordx4 v[32:35], v[6:7], off offset:16
	v_add_u32_e32 v8, s38, v8
	v_lshl_add_u64 v[6:7], v[6:7], 0, s[6:7]
	global_load_dwordx4 v[36:39], v[6:7], off
	global_load_dwordx4 v[40:43], v[6:7], off offset:16
	v_add_u32_e32 v8, s38, v8
	v_lshl_add_u64 v[6:7], v[6:7], 0, s[6:7]
	global_load_dwordx4 v[44:47], v[6:7], off
	global_load_dwordx4 v[48:51], v[6:7], off offset:16
	v_add_u32_e32 v8, s38, v8
	v_lshl_add_u64 v[6:7], v[6:7], 0, s[6:7]
	global_load_dwordx4 v[52:55], v[6:7], off
	global_load_dwordx4 v[56:59], v[6:7], off offset:16
	v_add_u32_e32 v8, s38, v8
	v_lshl_add_u64 v[6:7], v[6:7], 0, s[6:7]
	global_load_dwordx4 v[60:63], v[6:7], off
	global_load_dwordx4 v[64:67], v[6:7], off offset:16
	v_add_u32_e32 v8, s38, v8
	v_lshl_add_u64 v[6:7], v[6:7], 0, s[6:7]
	global_load_dwordx4 v[68:71], v[6:7], off
	global_load_dwordx4 v[72:75], v[6:7], off offset:16
	v_add_u32_e32 v8, s38, v8
	v_lshl_add_u64 v[6:7], v[6:7], 0, s[6:7]
	global_load_dwordx4 v[76:79], v[6:7], off
	global_load_dwordx4 v[80:83], v[6:7], off offset:16
	v_add_u32_e32 v8, s38, v8
	v_lshl_add_u64 v[6:7], v[6:7], 0, s[6:7]
	v_cmp_lt_i32_e32 vcc, s12, v8
	s_or_b64 s[8:9], vcc, s[8:9]
	s_waitcnt vmcnt(14)
	v_cvt_pk_bf16_f32 v20, v20, v21
	v_cvt_pk_bf16_f32 v21, v22, v23
	v_cvt_pk_bf16_f32 v22, v24, v25
	v_cvt_pk_bf16_f32 v23, v26, v27
	global_store_dwordx4 v[4:5], v[20:23], off
	v_lshl_add_u64 v[4:5], v[4:5], 0, s[4:5]
	s_waitcnt vmcnt(13)
	v_cvt_pk_bf16_f32 v28, v28, v29
	v_cvt_pk_bf16_f32 v29, v30, v31
	v_cvt_pk_bf16_f32 v30, v32, v33
	v_cvt_pk_bf16_f32 v31, v34, v35
	global_store_dwordx4 v[4:5], v[28:31], off
	v_lshl_add_u64 v[4:5], v[4:5], 0, s[4:5]
	s_waitcnt vmcnt(12)
	v_cvt_pk_bf16_f32 v36, v36, v37
	v_cvt_pk_bf16_f32 v37, v38, v39
	v_cvt_pk_bf16_f32 v38, v40, v41
	v_cvt_pk_bf16_f32 v39, v42, v43
	global_store_dwordx4 v[4:5], v[36:39], off
	v_lshl_add_u64 v[4:5], v[4:5], 0, s[4:5]
	s_waitcnt vmcnt(11)
	v_cvt_pk_bf16_f32 v44, v44, v45
	v_cvt_pk_bf16_f32 v45, v46, v47
	v_cvt_pk_bf16_f32 v46, v48, v49
	v_cvt_pk_bf16_f32 v47, v50, v51
	global_store_dwordx4 v[4:5], v[44:47], off
	v_lshl_add_u64 v[4:5], v[4:5], 0, s[4:5]
	s_waitcnt vmcnt(10)
	v_cvt_pk_bf16_f32 v52, v52, v53
	v_cvt_pk_bf16_f32 v53, v54, v55
	v_cvt_pk_bf16_f32 v54, v56, v57
	v_cvt_pk_bf16_f32 v55, v58, v59
	global_store_dwordx4 v[4:5], v[52:55], off
	v_lshl_add_u64 v[4:5], v[4:5], 0, s[4:5]
	s_waitcnt vmcnt(9)
	v_cvt_pk_bf16_f32 v60, v60, v61
	v_cvt_pk_bf16_f32 v61, v62, v63
	v_cvt_pk_bf16_f32 v62, v64, v65
	v_cvt_pk_bf16_f32 v63, v66, v67
	global_store_dwordx4 v[4:5], v[60:63], off
	v_lshl_add_u64 v[4:5], v[4:5], 0, s[4:5]
	s_waitcnt vmcnt(8)
	v_cvt_pk_bf16_f32 v68, v68, v69
	v_cvt_pk_bf16_f32 v69, v70, v71
	v_cvt_pk_bf16_f32 v70, v72, v73
	v_cvt_pk_bf16_f32 v71, v74, v75
	global_store_dwordx4 v[4:5], v[68:71], off
	v_lshl_add_u64 v[4:5], v[4:5], 0, s[4:5]
	s_waitcnt vmcnt(7)
	v_cvt_pk_bf16_f32 v76, v76, v77
	v_cvt_pk_bf16_f32 v77, v78, v79
	v_cvt_pk_bf16_f32 v78, v80, v81
	v_cvt_pk_bf16_f32 v79, v82, v83
	global_store_dwordx4 v[4:5], v[76:79], off
	v_lshl_add_u64 v[4:5], v[4:5], 0, s[4:5]
	s_andn2_b64 exec, exec, s[8:9]
	s_cbranch_execnz .LBB0_109

.LBB0_432:
	v_lshl_add_u64 v[4:5], v[2:3], 0, s[8:9]
	s_mov_b32 s0, 0x4c00000
	v_add_co_u32_e64 v16, s[0:1], s0, v4
	s_mov_b32 s11, 0x4c08000
	s_nop 0
	v_addc_co_u32_e64 v17, s[0:1], 0, v5, s[0:1]
	v_add_co_u32_e64 v18, s[0:1], s11, v4
	s_mov_b32 s12, 0x4c10000
	s_nop 0
	v_addc_co_u32_e64 v19, s[0:1], 0, v5, s[0:1]
	v_add_co_u32_e64 v20, s[0:1], s12, v4
	s_mov_b32 s13, 0x4c18000
	s_nop 0
	v_addc_co_u32_e64 v21, s[0:1], 0, v5, s[0:1]
	v_add_co_u32_e64 v22, s[0:1], s13, v4
	s_mov_b32 s14, 0x4c20000
	s_nop 0
	v_addc_co_u32_e64 v23, s[0:1], 0, v5, s[0:1]
	v_add_co_u32_e64 v24, s[0:1], s14, v4
	s_mov_b32 s15, 0x4c28000
	s_nop 0
	v_addc_co_u32_e64 v25, s[0:1], 0, v5, s[0:1]
	v_add_co_u32_e32 v14, vcc, 0x4bf0000, v4
	v_add_co_u32_e64 v26, s[0:1], s15, v4
	s_nop 0
	v_addc_co_u32_e32 v15, vcc, 0, v5, vcc
	v_addc_co_u32_e64 v27, s[0:1], 0, v5, s[0:1]
	s_mov_b32 s10, 0x4bf8000
	global_load_dwordx2 v[28:29], v[20:21], off
	global_load_dwordx2 v[30:31], v[22:23], off
	global_load_dwordx2 v[32:33], v[24:25], off
	global_load_dwordx2 v[34:35], v[26:27], off
	global_load_dwordx2 v[36:37], v[14:15], off
	v_add_co_u32_e32 v4, vcc, s10, v4
	v_cvt_pk_bf16_f32 v6, v10, v13
	s_nop 0
	v_addc_co_u32_e32 v5, vcc, 0, v5, vcc
	global_load_dwordx2 v[38:39], v[4:5], off
	global_load_dwordx2 v[40:41], v[16:17], off
	global_load_dwordx2 v[42:43], v[18:19], off
	v_cvt_pk_bf16_f32 v7, v12, v11
	global_store_dwordx2 v[14:15], v[6:7], off
	s_add_u32 s8, s8, 0x40000
	s_addc_u32 s9, s9, 0
	v_lshl_add_u64 v[64:65], v[2:3], 0, s[8:9]
	s_mov_b32 s0, 0x4c00000
	v_add_co_u32_e64 v76, s[0:1], s0, v64
	s_mov_b32 s11, 0x4c08000
	s_nop 0
	v_addc_co_u32_e64 v77, s[0:1], 0, v65, s[0:1]
	v_add_co_u32_e64 v78, s[0:1], s11, v64
	s_mov_b32 s12, 0x4c10000
	s_nop 0
	v_addc_co_u32_e64 v79, s[0:1], 0, v65, s[0:1]
	v_add_co_u32_e64 v80, s[0:1], s12, v64
	s_mov_b32 s13, 0x4c18000
	s_nop 0
	v_addc_co_u32_e64 v81, s[0:1], 0, v65, s[0:1]
	v_add_co_u32_e64 v82, s[0:1], s13, v64
	s_mov_b32 s14, 0x4c20000
	s_nop 0
	v_addc_co_u32_e64 v83, s[0:1], 0, v65, s[0:1]
	v_add_co_u32_e64 v84, s[0:1], s14, v64
	s_mov_b32 s15, 0x4c28000
	s_nop 0
	v_addc_co_u32_e64 v85, s[0:1], 0, v65, s[0:1]
	v_add_co_u32_e32 v74, vcc, 0x4bf0000, v64
	v_add_co_u32_e64 v86, s[0:1], s15, v64
	s_nop 0
	v_addc_co_u32_e32 v75, vcc, 0, v65, vcc
	v_addc_co_u32_e64 v87, s[0:1], 0, v65, s[0:1]
	s_mov_b32 s10, 0x4bf8000
	global_load_dwordx2 v[88:89], v[80:81], off
	global_load_dwordx2 v[90:91], v[82:83], off
	global_load_dwordx2 v[92:93], v[84:85], off
	global_load_dwordx2 v[94:95], v[86:87], off
	global_load_dwordx2 v[96:97], v[74:75], off
	v_add_co_u32_e32 v64, vcc, s10, v64
	s_nop 0
	v_addc_co_u32_e32 v65, vcc, 0, v65, vcc
	global_load_dwordx2 v[98:99], v[64:65], off
	global_load_dwordx2 v[100:101], v[76:77], off
	global_load_dwordx2 v[102:103], v[78:79], off
	s_waitcnt vmcnt(9)
	v_lshlrev_b32_e32 v14, 16, v28
	v_and_b32_e32 v15, 0xffff0000, v28
	v_lshlrev_b32_e32 v28, 16, v29
	v_and_b32_e32 v29, 0xffff0000, v29
	v_lshlrev_b32_e32 v48, 16, v36
	v_and_b32_e32 v36, 0xffff0000, v36
	v_lshlrev_b32_e32 v49, 16, v37
	v_and_b32_e32 v37, 0xffff0000, v37
	v_fmac_f32_e32 v48, v9, v10
	v_fmac_f32_e32 v36, v9, v13
	v_fmac_f32_e32 v49, v9, v12
	v_fmac_f32_e32 v37, v9, v11
	v_lshlrev_b32_e32 v50, 16, v38
	v_and_b32_e32 v38, 0xffff0000, v38
	v_lshlrev_b32_e32 v51, 16, v39
	v_and_b32_e32 v39, 0xffff0000, v39
	v_lshlrev_b32_e32 v52, 16, v40
	v_and_b32_e32 v40, 0xffff0000, v40
	v_lshlrev_b32_e32 v53, 16, v41
	v_and_b32_e32 v41, 0xffff0000, v41
	v_cvt_pk_bf16_f32 v6, v48, v36
	v_cvt_pk_bf16_f32 v7, v49, v37
	v_fmac_f32_e32 v50, v9, v48
	v_fmac_f32_e32 v38, v9, v36
	v_fmac_f32_e32 v51, v9, v49
	v_fmac_f32_e32 v39, v9, v37
	v_lshlrev_b32_e32 v54, 16, v42
	v_and_b32_e32 v42, 0xffff0000, v42
	v_lshlrev_b32_e32 v55, 16, v43
	v_and_b32_e32 v43, 0xffff0000, v43
	global_store_dwordx2 v[4:5], v[6:7], off
	v_cvt_pk_bf16_f32 v4, v50, v38
	v_cvt_pk_bf16_f32 v5, v51, v39
	v_fmac_f32_e32 v52, v9, v50
	v_fmac_f32_e32 v40, v9, v38
	v_fmac_f32_e32 v53, v9, v51
	v_fmac_f32_e32 v41, v9, v39
	global_store_dwordx2 v[16:17], v[4:5], off
	v_cvt_pk_bf16_f32 v4, v52, v40
	v_cvt_pk_bf16_f32 v5, v53, v41
	v_fmac_f32_e32 v54, v9, v52
	v_fmac_f32_e32 v42, v9, v40
	v_fmac_f32_e32 v55, v9, v53
	v_fmac_f32_e32 v43, v9, v41
	v_lshlrev_b32_e32 v44, 16, v30
	v_and_b32_e32 v30, 0xffff0000, v30
	v_lshlrev_b32_e32 v45, 16, v31
	v_and_b32_e32 v31, 0xffff0000, v31
	global_store_dwordx2 v[18:19], v[4:5], off
	v_cvt_pk_bf16_f32 v4, v54, v42
	v_cvt_pk_bf16_f32 v5, v55, v43
	v_fmac_f32_e32 v14, v9, v54
	v_fmac_f32_e32 v15, v9, v42
	v_fmac_f32_e32 v28, v9, v55
	v_fmac_f32_e32 v29, v9, v43
	v_lshlrev_b32_e32 v46, 16, v32
	v_and_b32_e32 v32, 0xffff0000, v32
	v_lshlrev_b32_e32 v47, 16, v33
	v_and_b32_e32 v33, 0xffff0000, v33
	global_store_dwordx2 v[20:21], v[4:5], off
	v_cvt_pk_bf16_f32 v4, v14, v15
	v_cvt_pk_bf16_f32 v5, v28, v29
	v_fmac_f32_e32 v44, v9, v14
	v_fmac_f32_e32 v30, v9, v15
	v_fmac_f32_e32 v45, v9, v28
	v_fmac_f32_e32 v31, v9, v29
	v_lshlrev_b32_e32 v10, 16, v34
	v_and_b32_e32 v13, 0xffff0000, v34
	v_lshlrev_b32_e32 v12, 16, v35
	v_and_b32_e32 v11, 0xffff0000, v35
	global_store_dwordx2 v[22:23], v[4:5], off
	v_cvt_pk_bf16_f32 v4, v44, v30
	v_cvt_pk_bf16_f32 v5, v45, v31
	v_fmac_f32_e32 v46, v9, v44
	v_fmac_f32_e32 v32, v9, v30
	v_fmac_f32_e32 v47, v9, v45
	v_fmac_f32_e32 v33, v9, v31
	global_store_dwordx2 v[24:25], v[4:5], off
	v_cvt_pk_bf16_f32 v4, v46, v32
	v_cvt_pk_bf16_f32 v5, v47, v33
	v_fmac_f32_e32 v10, v9, v46
	v_fmac_f32_e32 v13, v9, v32
	v_fmac_f32_e32 v12, v9, v47
	v_fmac_f32_e32 v11, v9, v33
	global_store_dwordx2 v[26:27], v[4:5], off
	v_cvt_pk_bf16_f32 v66, v10, v13
	v_cvt_pk_bf16_f32 v67, v12, v11
	global_store_dwordx2 v[74:75], v[66:67], off
	s_waitcnt vmcnt(8)
	v_lshlrev_b32_e32 v74, 16, v88
	v_and_b32_e32 v75, 0xffff0000, v88
	v_lshlrev_b32_e32 v88, 16, v89
	v_and_b32_e32 v89, 0xffff0000, v89
	v_lshlrev_b32_e32 v108, 16, v96
	v_and_b32_e32 v96, 0xffff0000, v96
	v_lshlrev_b32_e32 v109, 16, v97
	v_and_b32_e32 v97, 0xffff0000, v97
	v_fmac_f32_e32 v108, v9, v10
	v_fmac_f32_e32 v96, v9, v13
	v_fmac_f32_e32 v109, v9, v12
	v_fmac_f32_e32 v97, v9, v11
	v_lshlrev_b32_e32 v110, 16, v98
	v_and_b32_e32 v98, 0xffff0000, v98
	v_lshlrev_b32_e32 v111, 16, v99
	v_and_b32_e32 v99, 0xffff0000, v99
	v_lshlrev_b32_e32 v112, 16, v100
	v_and_b32_e32 v100, 0xffff0000, v100
	v_lshlrev_b32_e32 v113, 16, v101
	v_and_b32_e32 v101, 0xffff0000, v101
	v_cvt_pk_bf16_f32 v66, v108, v96
	v_cvt_pk_bf16_f32 v67, v109, v97
	v_fmac_f32_e32 v110, v9, v108
	v_fmac_f32_e32 v98, v9, v96
	v_fmac_f32_e32 v111, v9, v109
	v_fmac_f32_e32 v99, v9, v97
	v_lshlrev_b32_e32 v114, 16, v102
	v_and_b32_e32 v102, 0xffff0000, v102
	v_lshlrev_b32_e32 v115, 16, v103
	v_and_b32_e32 v103, 0xffff0000, v103
	global_store_dwordx2 v[64:65], v[66:67], off
	v_cvt_pk_bf16_f32 v64, v110, v98
	v_cvt_pk_bf16_f32 v65, v111, v99
	v_fmac_f32_e32 v112, v9, v110
	v_fmac_f32_e32 v100, v9, v98
	v_fmac_f32_e32 v113, v9, v111
	v_fmac_f32_e32 v101, v9, v99
	global_store_dwordx2 v[76:77], v[64:65], off
	v_cvt_pk_bf16_f32 v64, v112, v100
	v_cvt_pk_bf16_f32 v65, v113, v101
	v_fmac_f32_e32 v114, v9, v112
	v_fmac_f32_e32 v102, v9, v100
	v_fmac_f32_e32 v115, v9, v113
	v_fmac_f32_e32 v103, v9, v101
	v_lshlrev_b32_e32 v104, 16, v90
	v_and_b32_e32 v90, 0xffff0000, v90
	v_lshlrev_b32_e32 v105, 16, v91
	v_and_b32_e32 v91, 0xffff0000, v91
	global_store_dwordx2 v[78:79], v[64:65], off
	v_cvt_pk_bf16_f32 v64, v114, v102
	v_cvt_pk_bf16_f32 v65, v115, v103
	v_fmac_f32_e32 v74, v9, v114
	v_fmac_f32_e32 v75, v9, v102
	v_fmac_f32_e32 v88, v9, v115
	v_fmac_f32_e32 v89, v9, v103
	v_lshlrev_b32_e32 v106, 16, v92
	v_and_b32_e32 v92, 0xffff0000, v92
	v_lshlrev_b32_e32 v107, 16, v93
	v_and_b32_e32 v93, 0xffff0000, v93
	global_store_dwordx2 v[80:81], v[64:65], off
	v_cvt_pk_bf16_f32 v64, v74, v75
	v_cvt_pk_bf16_f32 v65, v88, v89
	v_fmac_f32_e32 v104, v9, v74
	v_fmac_f32_e32 v90, v9, v75
	v_fmac_f32_e32 v105, v9, v88
	v_fmac_f32_e32 v91, v9, v89
	v_lshlrev_b32_e32 v10, 16, v94
	v_and_b32_e32 v13, 0xffff0000, v94
	v_lshlrev_b32_e32 v12, 16, v95
	v_and_b32_e32 v11, 0xffff0000, v95
	global_store_dwordx2 v[82:83], v[64:65], off
	v_cvt_pk_bf16_f32 v64, v104, v90
	v_cvt_pk_bf16_f32 v65, v105, v91
	v_fmac_f32_e32 v106, v9, v104
	v_fmac_f32_e32 v92, v9, v90
	v_fmac_f32_e32 v107, v9, v105
	v_fmac_f32_e32 v93, v9, v91
	global_store_dwordx2 v[84:85], v[64:65], off
	v_cvt_pk_bf16_f32 v64, v106, v92
	v_cvt_pk_bf16_f32 v65, v107, v93
	v_fmac_f32_e32 v10, v9, v106
	v_fmac_f32_e32 v13, v9, v92
	v_fmac_f32_e32 v12, v9, v107
	v_fmac_f32_e32 v11, v9, v93
	global_store_dwordx2 v[86:87], v[64:65], off
	s_add_u32 s8, s8, 0x40000
	s_addc_u32 s9, s9, 0
	s_cmp_eq_u32 s8, 0x200000
	s_cbranch_scc0 .LBB0_432
	v_add_u32_e32 v0, s38, v0
	v_cmp_lt_i32_e32 vcc, s66, v0
	s_or_b64 s[6:7], vcc, s[6:7]
	v_add_u16_e32 v8, s38, v8
	s_andn2_b64 exec, exec, s[6:7]
	s_cbranch_execnz .LBB0_431
